# grid barrier: XCD leader bumps the per-XCD generation before its own buffer_inv (10 sites), on top of v43
# baseline (speedup 1.0000x reference)
; __device__ __forceinline__ unsigned xb_add(unsigned* p, unsigned v) { return __hip_atomic_fetch_add(p, v, __ATOMIC_RELAXED, __HIP_MEMORY_SCOPE_AGENT); }
; __device__ __forceinline__ void xcd_barrier(const XcdBarrier& b) {
;     ...
;             __builtin_amdgcn_fence(__ATOMIC_ACQUIRE, "agent");
;             xb_add(&bar[XB_XGEN(b.x)], 1u);
;             asm volatile("s_waitcnt vmcnt(0)" ::: "memory");
.LBB0_158:
	s_or_b64 exec, exec, s[12:13]
	s_mov_b64 s[12:13], exec
	v_mbcnt_lo_u32_b32 v1, s12, 0
	v_mbcnt_hi_u32_b32 v1, s13, v1
	v_cmp_eq_u32_e32 vcc, 0, v1
	s_waitcnt vmcnt(0)
	s_and_saveexec_b64 s[14:15], vcc
	s_cbranch_execz .LBB0_160
	s_bcnt1_i32_b64 s2, s[12:13]
	v_mov_b32_e32 v1, 0x2000
	v_mov_b32_e32 v2, s2
	global_atomic_add v1, v2, s[8:9] offset:1024
.LBB0_160:
	s_or_b64 exec, exec, s[14:15]
	buffer_inv sc1
	s_waitcnt vmcnt(0)

; __device__ __forceinline__ unsigned xb_add(unsigned* p, unsigned v) { return __hip_atomic_fetch_add(p, v, __ATOMIC_RELAXED, __HIP_MEMORY_SCOPE_AGENT); }
; __device__ __forceinline__ void xcd_barrier(const XcdBarrier& b) {
;     ...
;             __builtin_amdgcn_fence(__ATOMIC_ACQUIRE, "agent");
;             xb_add(&bar[XB_XGEN(b.x)], 1u);
;             asm volatile("s_waitcnt vmcnt(0)" ::: "memory");
.LBB0_2036:
	s_or_b64 exec, exec, s[14:15]
	s_mov_b64 s[14:15], exec
	v_mbcnt_lo_u32_b32 v1, s14, 0
	v_mbcnt_hi_u32_b32 v1, s15, v1
	v_cmp_eq_u32_e32 vcc, 0, v1
	s_waitcnt vmcnt(0)
	s_and_saveexec_b64 s[16:17], vcc
	s_cbranch_execz .LBB0_2038
	s_bcnt1_i32_b64 s2, s[14:15]
	v_mov_b32_e32 v1, 0x2000
	v_mov_b32_e32 v2, s2
	global_atomic_add v1, v2, s[8:9] offset:1024
.LBB0_2038:
	s_or_b64 exec, exec, s[16:17]
	buffer_inv sc1
	s_waitcnt vmcnt(0)

; __device__ __forceinline__ unsigned xb_add(unsigned* p, unsigned v) { return __hip_atomic_fetch_add(p, v, __ATOMIC_RELAXED, __HIP_MEMORY_SCOPE_AGENT); }
; __device__ __forceinline__ void xcd_barrier(const XcdBarrier& b) {
;     ...
;             __builtin_amdgcn_fence(__ATOMIC_ACQUIRE, "agent");
;             xb_add(&bar[XB_XGEN(b.x)], 1u);
;             asm volatile("s_waitcnt vmcnt(0)" ::: "memory");
.LBB0_2166:
	s_or_b64 exec, exec, s[10:11]
	s_mov_b64 s[10:11], exec
	v_mbcnt_lo_u32_b32 v1, s10, 0
	v_mbcnt_hi_u32_b32 v1, s11, v1
	v_cmp_eq_u32_e32 vcc, 0, v1
	s_waitcnt vmcnt(0)
	s_and_saveexec_b64 s[12:13], vcc
	s_cbranch_execz .LBB0_2168
	s_bcnt1_i32_b64 s2, s[10:11]
	v_mov_b32_e32 v1, 0x2000
	v_mov_b32_e32 v2, s2
	global_atomic_add v1, v2, s[6:7] offset:1024
.LBB0_2168:
	s_or_b64 exec, exec, s[12:13]
	buffer_inv sc1
	s_waitcnt vmcnt(0)
